# pool_item history-window loads issued back to back with one wait; barrier after prep: GEMM blocks arrive without waiting; barrier after phase A: scan blocks arrive without waiting
# baseline (speedup 1.0000x reference)
; __device__ __forceinline__ unsigned xb_ld(unsigned* p)              { return __hip_atomic_load(p, __ATOMIC_RELAXED, __HIP_MEMORY_SCOPE_AGENT); }
; __device__ __forceinline__ unsigned xb_add(unsigned* p, unsigned v) { return __hip_atomic_fetch_add(p, v, __ATOMIC_RELAXED, __HIP_MEMORY_SCOPE_AGENT); }
; #define XB_SPIN(cond, bar) do { unsigned _sp = 0; while (cond) { __builtin_amdgcn_s_sleep(1); \
;     if ((++_sp & 255u) == 0u) { if (xb_ld(&(bar)[XB_TMO])) break; if (_sp > XB_SPIN_CAP) { atomicAdd(&(bar)[XB_TMO], 1u); break; } } } } while (0)
; __device__ __forceinline__ void xcd_barrier(const XcdBarrier& b) {
;     ...
;         const unsigned old = xb_add(&bar[XB_XSUB(b.x)], 1u);
;         const unsigned gen = old / nloc;
;         if (old + 1u == (gen + 1u) * nloc) {
;             __builtin_amdgcn_fence(__ATOMIC_RELEASE, "agent");
;             asm volatile("s_waitcnt vmcnt(0)" ::: "memory");
;             const unsigned og = xb_add(&bar[XB_TOP], 1u);
;             const unsigned tg = og / nx;
;             if (og + 1u == (tg + 1u) * nx) xb_add(&bar[XB_TOPGEN], 1u);
;             else XB_SPIN(xb_ld(&bar[XB_TOPGEN]) == tg, bar);
;             __builtin_amdgcn_fence(__ATOMIC_ACQUIRE, "agent");
;             xb_add(&bar[XB_XGEN(b.x)], 1u);
;             asm volatile("s_waitcnt vmcnt(0)" ::: "memory");
;         } else {
;             XB_SPIN(xb_ld(&bar[XB_XGEN(b.x)]) == gen, bar);
.LBB0_1416:
	s_or_b64 exec, exec, s[10:11]
	v_cvt_f32_u32_e32 v4, v2
	s_waitcnt vmcnt(0)
	v_readfirstlane_b32 s0, v3
	v_sub_u32_e32 v3, 0, v2
	v_rcp_iflag_f32_e32 v4, v4
	v_add_u32_e32 v5, s0, v1
	v_mul_f32_e32 v4, 0x4f7ffffe, v4
	v_cvt_u32_f32_e32 v4, v4
	v_mul_lo_u32 v1, v3, v4
	v_mul_hi_u32 v1, v4, v1
	v_add_u32_e32 v1, v4, v1
	v_mul_hi_u32 v1, v5, v1
	v_mul_lo_u32 v3, v1, v2
	v_sub_u32_e32 v3, v5, v3
	v_add_u32_e32 v4, 1, v1
	v_cmp_ge_u32_e32 vcc, v3, v2
	s_nop 1
	v_cndmask_b32_e32 v1, v1, v4, vcc
	v_sub_u32_e32 v4, v3, v2
	v_cndmask_b32_e32 v3, v3, v4, vcc
	v_add_u32_e32 v4, 1, v1
	v_cmp_ge_u32_e32 vcc, v3, v2
	v_add_u32_e32 v3, 1, v5
	s_nop 0
	v_cndmask_b32_e32 v1, v1, v4, vcc
	v_mul_lo_u32 v4, v2, v1
	v_add_u32_e32 v2, v4, v2
	v_cmp_ne_u32_e32 vcc, v3, v2
	s_and_saveexec_b64 s[0:1], vcc
	s_xor_b64 s[8:9], exec, s[0:1]
	s_cbranch_execz .LBB0_1430
	s_waitcnt lgkmcnt(0)
	s_cmp_lt_i32 s92, 64
	s_cbranch_scc1 .LBB0_1430
	v_mov_b32_e32 v0, 0x2000
	global_load_dword v0, v0, s[6:7] offset:1024 sc1
	s_add_u32 s62, s6, 0x2400
	s_addc_u32 s63, s7, 0
	s_waitcnt vmcnt(0)
	v_cmp_eq_u32_e32 vcc, v0, v1
	s_and_saveexec_b64 s[10:11], vcc
	s_cbranch_execz .LBB0_1429
	s_mov_b32 s0, 1
	s_mov_b64 s[66:67], 0
	v_mov_b32_e32 v0, 0
	s_branch .LBB0_1420

; __device__ __forceinline__ float lo_bf(unsigned w) { return __uint_as_float(w << 16); }
; __device__ __forceinline__ float hi_bf(unsigned w) { return __uint_as_float(w & 0xffff0000u); }
; __device__ __forceinline__ void pool_item(const Params& P, int l, int item, unsigned char* smem) {
;     ...
; #pragma unroll
;                 for (int k = 0; k < WIN - 1 + 16; ++k) {
;                     const int dt = k - (WIN - 1), t = t0 + dt;
;                     if (t >= 0) { const unsigned wv = *(const unsigned*)(proj + (size_t)(R0 + dt) * NIN + c); u0[k] = lo_bf(wv); u1[k] = hi_bf(wv); }
;                     else if (hist) { const float* hp = hist + (size_t)(15 + t) * 1024 + c; u0[k] = hp[0]; u1[k] = hp[1]; }
;                     else { u0[k] = 0.f; u1[k] = 0.f; }
;                 }
.LBB0_1526:
	s_or_b64 exec, exec, s[4:5]
	v_cmp_ne_u64_e64 s[4:5], 0, v[34:35]
	v_cmp_ne_u32_e64 s[6:7], 0, v37
	s_and_saveexec_b64 s[10:11], s[6:7]
	s_xor_b64 s[10:11], exec, s[10:11]
	s_cbranch_execz .LBB0_1556
	v_add_u32_e32 v4, -15, v39
	v_mad_i64_i32 v[4:5], s[28:29], v4, s15, v[0:1]
	global_load_dword v5, v[4:5], off
	s_andn2_saveexec_b64 s[10:11], s[10:11]
	s_cbranch_execnz .LBB0_1557

; __device__ __forceinline__ float lo_bf(unsigned w) { return __uint_as_float(w << 16); }
; __device__ __forceinline__ float hi_bf(unsigned w) { return __uint_as_float(w & 0xffff0000u); }
; __device__ __forceinline__ void pool_item(const Params& P, int l, int item, unsigned char* smem) {
;     ...
; #pragma unroll
;                 for (int k = 0; k < WIN - 1 + 16; ++k) {
;                     const int dt = k - (WIN - 1), t = t0 + dt;
;                     if (t >= 0) { const unsigned wv = *(const unsigned*)(proj + (size_t)(R0 + dt) * NIN + c); u0[k] = lo_bf(wv); u1[k] = hi_bf(wv); }
;                     else if (hist) { const float* hp = hist + (size_t)(15 + t) * 1024 + c; u0[k] = hp[0]; u1[k] = hp[1]; }
;                     else { u0[k] = 0.f; u1[k] = 0.f; }
;                 }
.LBB0_1529:
	v_add_u32_e32 v6, -14, v39
	v_mad_i64_i32 v[6:7], s[28:29], v6, s15, v[0:1]
	global_load_dword v7, v[6:7], off
	s_andn2_saveexec_b64 s[10:11], s[10:11]
	s_cbranch_execnz .LBB0_1561

; __device__ __forceinline__ float lo_bf(unsigned w) { return __uint_as_float(w << 16); }
; __device__ __forceinline__ float hi_bf(unsigned w) { return __uint_as_float(w & 0xffff0000u); }
; __device__ __forceinline__ void pool_item(const Params& P, int l, int item, unsigned char* smem) {
;     ...
; #pragma unroll
;                 for (int k = 0; k < WIN - 1 + 16; ++k) {
;                     const int dt = k - (WIN - 1), t = t0 + dt;
;                     if (t >= 0) { const unsigned wv = *(const unsigned*)(proj + (size_t)(R0 + dt) * NIN + c); u0[k] = lo_bf(wv); u1[k] = hi_bf(wv); }
;                     else if (hist) { const float* hp = hist + (size_t)(15 + t) * 1024 + c; u0[k] = hp[0]; u1[k] = hp[1]; }
;                     else { u0[k] = 0.f; u1[k] = 0.f; }
;                 }
.LBB0_1531:
	v_add_u32_e32 v8, -13, v39
	v_mad_i64_i32 v[8:9], s[28:29], v8, s15, v[0:1]
	global_load_dword v9, v[8:9], off
	s_andn2_saveexec_b64 s[10:11], s[10:11]
	s_cbranch_execnz .LBB0_1565

; __device__ __forceinline__ float lo_bf(unsigned w) { return __uint_as_float(w << 16); }
; __device__ __forceinline__ float hi_bf(unsigned w) { return __uint_as_float(w & 0xffff0000u); }
; __device__ __forceinline__ void pool_item(const Params& P, int l, int item, unsigned char* smem) {
;     ...
; #pragma unroll
;                 for (int k = 0; k < WIN - 1 + 16; ++k) {
;                     const int dt = k - (WIN - 1), t = t0 + dt;
;                     if (t >= 0) { const unsigned wv = *(const unsigned*)(proj + (size_t)(R0 + dt) * NIN + c); u0[k] = lo_bf(wv); u1[k] = hi_bf(wv); }
;                     else if (hist) { const float* hp = hist + (size_t)(15 + t) * 1024 + c; u0[k] = hp[0]; u1[k] = hp[1]; }
;                     else { u0[k] = 0.f; u1[k] = 0.f; }
;                 }
.LBB0_1533:
	v_add_u32_e32 v10, -12, v39
	v_mad_i64_i32 v[10:11], s[28:29], v10, s15, v[0:1]
	global_load_dword v11, v[10:11], off
	s_andn2_saveexec_b64 s[10:11], s[10:11]
	s_cbranch_execnz .LBB0_1569

; __device__ __forceinline__ float lo_bf(unsigned w) { return __uint_as_float(w << 16); }
; __device__ __forceinline__ float hi_bf(unsigned w) { return __uint_as_float(w & 0xffff0000u); }
; __device__ __forceinline__ void pool_item(const Params& P, int l, int item, unsigned char* smem) {
;     ...
; #pragma unroll
;                 for (int k = 0; k < WIN - 1 + 16; ++k) {
;                     const int dt = k - (WIN - 1), t = t0 + dt;
;                     if (t >= 0) { const unsigned wv = *(const unsigned*)(proj + (size_t)(R0 + dt) * NIN + c); u0[k] = lo_bf(wv); u1[k] = hi_bf(wv); }
;                     else if (hist) { const float* hp = hist + (size_t)(15 + t) * 1024 + c; u0[k] = hp[0]; u1[k] = hp[1]; }
;                     else { u0[k] = 0.f; u1[k] = 0.f; }
;                 }
.LBB0_1535:
	v_add_u32_e32 v12, -11, v39
	v_mad_i64_i32 v[12:13], s[28:29], v12, s15, v[0:1]
	global_load_dword v13, v[12:13], off
	s_andn2_saveexec_b64 s[10:11], s[10:11]
	s_cbranch_execnz .LBB0_1573

; __device__ __forceinline__ float lo_bf(unsigned w) { return __uint_as_float(w << 16); }
; __device__ __forceinline__ float hi_bf(unsigned w) { return __uint_as_float(w & 0xffff0000u); }
; __device__ __forceinline__ void pool_item(const Params& P, int l, int item, unsigned char* smem) {
;     ...
; #pragma unroll
;                 for (int k = 0; k < WIN - 1 + 16; ++k) {
;                     const int dt = k - (WIN - 1), t = t0 + dt;
;                     if (t >= 0) { const unsigned wv = *(const unsigned*)(proj + (size_t)(R0 + dt) * NIN + c); u0[k] = lo_bf(wv); u1[k] = hi_bf(wv); }
;                     else if (hist) { const float* hp = hist + (size_t)(15 + t) * 1024 + c; u0[k] = hp[0]; u1[k] = hp[1]; }
;                     else { u0[k] = 0.f; u1[k] = 0.f; }
;                 }
.LBB0_1537:
	v_add_u32_e32 v14, -10, v39
	v_mad_i64_i32 v[14:15], s[28:29], v14, s15, v[0:1]
	global_load_dword v15, v[14:15], off
	s_andn2_saveexec_b64 s[10:11], s[10:11]
	s_cbranch_execnz .LBB0_1577

; __device__ __forceinline__ float lo_bf(unsigned w) { return __uint_as_float(w << 16); }
; __device__ __forceinline__ float hi_bf(unsigned w) { return __uint_as_float(w & 0xffff0000u); }
; __device__ __forceinline__ void pool_item(const Params& P, int l, int item, unsigned char* smem) {
;     ...
; #pragma unroll
;                 for (int k = 0; k < WIN - 1 + 16; ++k) {
;                     const int dt = k - (WIN - 1), t = t0 + dt;
;                     if (t >= 0) { const unsigned wv = *(const unsigned*)(proj + (size_t)(R0 + dt) * NIN + c); u0[k] = lo_bf(wv); u1[k] = hi_bf(wv); }
;                     else if (hist) { const float* hp = hist + (size_t)(15 + t) * 1024 + c; u0[k] = hp[0]; u1[k] = hp[1]; }
;                     else { u0[k] = 0.f; u1[k] = 0.f; }
;                 }
.LBB0_1539:
	v_add_u32_e32 v16, -9, v39
	v_mad_i64_i32 v[16:17], s[28:29], v16, s15, v[0:1]
	global_load_dword v17, v[16:17], off
	s_andn2_saveexec_b64 s[10:11], s[10:11]
	s_cbranch_execnz .LBB0_1581

; __device__ __forceinline__ float lo_bf(unsigned w) { return __uint_as_float(w << 16); }
; __device__ __forceinline__ float hi_bf(unsigned w) { return __uint_as_float(w & 0xffff0000u); }
; __device__ __forceinline__ void pool_item(const Params& P, int l, int item, unsigned char* smem) {
;     ...
; #pragma unroll
;                 for (int k = 0; k < WIN - 1 + 16; ++k) {
;                     const int dt = k - (WIN - 1), t = t0 + dt;
;                     if (t >= 0) { const unsigned wv = *(const unsigned*)(proj + (size_t)(R0 + dt) * NIN + c); u0[k] = lo_bf(wv); u1[k] = hi_bf(wv); }
;                     else if (hist) { const float* hp = hist + (size_t)(15 + t) * 1024 + c; u0[k] = hp[0]; u1[k] = hp[1]; }
;                     else { u0[k] = 0.f; u1[k] = 0.f; }
;                 }
.LBB0_1541:
	v_add_u32_e32 v18, -8, v39
	v_mad_i64_i32 v[18:19], s[28:29], v18, s15, v[0:1]
	global_load_dword v19, v[18:19], off
	s_andn2_saveexec_b64 s[10:11], s[10:11]
	s_cbranch_execnz .LBB0_1585

; __device__ __forceinline__ float lo_bf(unsigned w) { return __uint_as_float(w << 16); }
; __device__ __forceinline__ float hi_bf(unsigned w) { return __uint_as_float(w & 0xffff0000u); }
; __device__ __forceinline__ void pool_item(const Params& P, int l, int item, unsigned char* smem) {
;     ...
; #pragma unroll
;                 for (int k = 0; k < WIN - 1 + 16; ++k) {
;                     const int dt = k - (WIN - 1), t = t0 + dt;
;                     if (t >= 0) { const unsigned wv = *(const unsigned*)(proj + (size_t)(R0 + dt) * NIN + c); u0[k] = lo_bf(wv); u1[k] = hi_bf(wv); }
;                     else if (hist) { const float* hp = hist + (size_t)(15 + t) * 1024 + c; u0[k] = hp[0]; u1[k] = hp[1]; }
;                     else { u0[k] = 0.f; u1[k] = 0.f; }
;                 }
.LBB0_1543:
	v_add_u32_e32 v20, -7, v39
	v_mad_i64_i32 v[20:21], s[28:29], v20, s15, v[0:1]
	global_load_dword v21, v[20:21], off
	s_andn2_saveexec_b64 s[10:11], s[10:11]
	s_cbranch_execnz .LBB0_1589

; __device__ __forceinline__ float lo_bf(unsigned w) { return __uint_as_float(w << 16); }
; __device__ __forceinline__ float hi_bf(unsigned w) { return __uint_as_float(w & 0xffff0000u); }
; __device__ __forceinline__ void pool_item(const Params& P, int l, int item, unsigned char* smem) {
;     ...
; #pragma unroll
;                 for (int k = 0; k < WIN - 1 + 16; ++k) {
;                     const int dt = k - (WIN - 1), t = t0 + dt;
;                     if (t >= 0) { const unsigned wv = *(const unsigned*)(proj + (size_t)(R0 + dt) * NIN + c); u0[k] = lo_bf(wv); u1[k] = hi_bf(wv); }
;                     else if (hist) { const float* hp = hist + (size_t)(15 + t) * 1024 + c; u0[k] = hp[0]; u1[k] = hp[1]; }
;                     else { u0[k] = 0.f; u1[k] = 0.f; }
;                 }
.LBB0_1545:
	v_add_u32_e32 v22, -6, v39
	v_mad_i64_i32 v[22:23], s[28:29], v22, s15, v[0:1]
	global_load_dword v23, v[22:23], off
	s_andn2_saveexec_b64 s[10:11], s[10:11]
	s_cbranch_execnz .LBB0_1593

; __device__ __forceinline__ float lo_bf(unsigned w) { return __uint_as_float(w << 16); }
; __device__ __forceinline__ float hi_bf(unsigned w) { return __uint_as_float(w & 0xffff0000u); }
; __device__ __forceinline__ void pool_item(const Params& P, int l, int item, unsigned char* smem) {
;     ...
; #pragma unroll
;                 for (int k = 0; k < WIN - 1 + 16; ++k) {
;                     const int dt = k - (WIN - 1), t = t0 + dt;
;                     if (t >= 0) { const unsigned wv = *(const unsigned*)(proj + (size_t)(R0 + dt) * NIN + c); u0[k] = lo_bf(wv); u1[k] = hi_bf(wv); }
;                     else if (hist) { const float* hp = hist + (size_t)(15 + t) * 1024 + c; u0[k] = hp[0]; u1[k] = hp[1]; }
;                     else { u0[k] = 0.f; u1[k] = 0.f; }
;                 }
.LBB0_1547:
	v_add_u32_e32 v24, -5, v39
	v_mad_i64_i32 v[24:25], s[28:29], v24, s15, v[0:1]
	global_load_dword v25, v[24:25], off
	s_andn2_saveexec_b64 s[10:11], s[10:11]
	s_cbranch_execnz .LBB0_1597

; __device__ __forceinline__ float lo_bf(unsigned w) { return __uint_as_float(w << 16); }
; __device__ __forceinline__ float hi_bf(unsigned w) { return __uint_as_float(w & 0xffff0000u); }
; __device__ __forceinline__ void pool_item(const Params& P, int l, int item, unsigned char* smem) {
;     ...
; #pragma unroll
;                 for (int k = 0; k < WIN - 1 + 16; ++k) {
;                     const int dt = k - (WIN - 1), t = t0 + dt;
;                     if (t >= 0) { const unsigned wv = *(const unsigned*)(proj + (size_t)(R0 + dt) * NIN + c); u0[k] = lo_bf(wv); u1[k] = hi_bf(wv); }
;                     else if (hist) { const float* hp = hist + (size_t)(15 + t) * 1024 + c; u0[k] = hp[0]; u1[k] = hp[1]; }
;                     else { u0[k] = 0.f; u1[k] = 0.f; }
;                 }
.LBB0_1549:
	v_add_u32_e32 v26, -4, v39
	v_mad_i64_i32 v[26:27], s[28:29], v26, s15, v[0:1]
	global_load_dword v27, v[26:27], off
	s_andn2_saveexec_b64 s[10:11], s[10:11]
	s_cbranch_execnz .LBB0_1601

; __device__ __forceinline__ float lo_bf(unsigned w) { return __uint_as_float(w << 16); }
; __device__ __forceinline__ float hi_bf(unsigned w) { return __uint_as_float(w & 0xffff0000u); }
; __device__ __forceinline__ void pool_item(const Params& P, int l, int item, unsigned char* smem) {
;     ...
; #pragma unroll
;                 for (int k = 0; k < WIN - 1 + 16; ++k) {
;                     const int dt = k - (WIN - 1), t = t0 + dt;
;                     if (t >= 0) { const unsigned wv = *(const unsigned*)(proj + (size_t)(R0 + dt) * NIN + c); u0[k] = lo_bf(wv); u1[k] = hi_bf(wv); }
;                     else if (hist) { const float* hp = hist + (size_t)(15 + t) * 1024 + c; u0[k] = hp[0]; u1[k] = hp[1]; }
;                     else { u0[k] = 0.f; u1[k] = 0.f; }
;                 }
.LBB0_1551:
	v_add_u32_e32 v28, -3, v39
	v_mad_i64_i32 v[28:29], s[28:29], v28, s15, v[0:1]
	global_load_dword v29, v[28:29], off
	s_andn2_saveexec_b64 s[10:11], s[10:11]
	s_cbranch_execnz .LBB0_1605

; __device__ __forceinline__ float lo_bf(unsigned w) { return __uint_as_float(w << 16); }
; __device__ __forceinline__ float hi_bf(unsigned w) { return __uint_as_float(w & 0xffff0000u); }
; __device__ __forceinline__ void pool_item(const Params& P, int l, int item, unsigned char* smem) {
;     ...
; #pragma unroll
;                 for (int k = 0; k < WIN - 1 + 16; ++k) {
;                     const int dt = k - (WIN - 1), t = t0 + dt;
;                     if (t >= 0) { const unsigned wv = *(const unsigned*)(proj + (size_t)(R0 + dt) * NIN + c); u0[k] = lo_bf(wv); u1[k] = hi_bf(wv); }
;                     else if (hist) { const float* hp = hist + (size_t)(15 + t) * 1024 + c; u0[k] = hp[0]; u1[k] = hp[1]; }
;                     else { u0[k] = 0.f; u1[k] = 0.f; }
;                 }
.LBB0_1553:
	v_add_u32_e32 v30, -2, v39
	v_mad_i64_i32 v[30:31], s[28:29], v30, s15, v[0:1]
	global_load_dword v31, v[30:31], off
	s_andn2_saveexec_b64 s[10:11], s[10:11]
	s_cbranch_execnz .LBB0_1609

; __device__ __forceinline__ float lo_bf(unsigned w) { return __uint_as_float(w << 16); }
; __device__ __forceinline__ float hi_bf(unsigned w) { return __uint_as_float(w & 0xffff0000u); }
; __device__ __forceinline__ void pool_item(const Params& P, int l, int item, unsigned char* smem) {
;     ...
; #pragma unroll
;                 for (int k = 0; k < WIN - 1 + 16; ++k) {
;                     const int dt = k - (WIN - 1), t = t0 + dt;
;                     if (t >= 0) { const unsigned wv = *(const unsigned*)(proj + (size_t)(R0 + dt) * NIN + c); u0[k] = lo_bf(wv); u1[k] = hi_bf(wv); }
;                     else if (hist) { const float* hp = hist + (size_t)(15 + t) * 1024 + c; u0[k] = hp[0]; u1[k] = hp[1]; }
;                     else { u0[k] = 0.f; u1[k] = 0.f; }
;                 }
.LBB0_1555:
	v_add_u32_e32 v32, -1, v39
	v_mad_i64_i32 v[32:33], s[10:11], v32, s15, v[0:1]
	global_load_dword v33, v[32:33], off
	s_waitcnt vmcnt(0)
	v_lshlrev_b32_e32 v4, 16, v5
	v_and_b32_e32 v5, 0xffff0000, v5
	v_lshlrev_b32_e32 v6, 16, v7
	v_and_b32_e32 v7, 0xffff0000, v7
	v_lshlrev_b32_e32 v8, 16, v9
	v_and_b32_e32 v9, 0xffff0000, v9
	v_lshlrev_b32_e32 v10, 16, v11
	v_and_b32_e32 v11, 0xffff0000, v11
	v_lshlrev_b32_e32 v12, 16, v13
	v_and_b32_e32 v13, 0xffff0000, v13
	v_lshlrev_b32_e32 v14, 16, v15
	v_and_b32_e32 v15, 0xffff0000, v15
	v_lshlrev_b32_e32 v16, 16, v17
	v_and_b32_e32 v17, 0xffff0000, v17
	v_lshlrev_b32_e32 v18, 16, v19
	v_and_b32_e32 v19, 0xffff0000, v19
	v_lshlrev_b32_e32 v20, 16, v21
	v_and_b32_e32 v21, 0xffff0000, v21
	v_lshlrev_b32_e32 v22, 16, v23
	v_and_b32_e32 v23, 0xffff0000, v23
	v_lshlrev_b32_e32 v24, 16, v25
	v_and_b32_e32 v25, 0xffff0000, v25
	v_lshlrev_b32_e32 v26, 16, v27
	v_and_b32_e32 v27, 0xffff0000, v27
	v_lshlrev_b32_e32 v28, 16, v29
	v_and_b32_e32 v29, 0xffff0000, v29
	v_lshlrev_b32_e32 v30, 16, v31
	v_and_b32_e32 v31, 0xffff0000, v31
	v_lshlrev_b32_e32 v32, 16, v33
	v_and_b32_e32 v33, 0xffff0000, v33
	s_andn2_saveexec_b64 s[6:7], s[6:7]
	s_cbranch_execz .LBB0_1521
	s_branch .LBB0_1613

; __device__ __forceinline__ float lo_bf(unsigned w) { return __uint_as_float(w << 16); }
; __device__ __forceinline__ float hi_bf(unsigned w) { return __uint_as_float(w & 0xffff0000u); }
; __device__ __forceinline__ void pool_item(const Params& P, int l, int item, unsigned char* smem) {
;     ...
; #pragma unroll
;                 for (int k = 0; k < WIN - 1 + 16; ++k) {
;                     const int dt = k - (WIN - 1), t = t0 + dt;
;                     if (t >= 0) { const unsigned wv = *(const unsigned*)(proj + (size_t)(R0 + dt) * NIN + c); u0[k] = lo_bf(wv); u1[k] = hi_bf(wv); }
;                     else if (hist) { const float* hp = hist + (size_t)(15 + t) * 1024 + c; u0[k] = hp[0]; u1[k] = hp[1]; }
;                     else { u0[k] = 0.f; u1[k] = 0.f; }
;                 }
.LBB0_1625:
	s_or_b64 exec, exec, s[4:5]
	v_cmp_ne_u64_e64 s[4:5], 0, v[18:19]
	v_cmp_ne_u32_e64 s[6:7], 0, v20
	s_and_saveexec_b64 s[10:11], s[6:7]
	s_xor_b64 s[10:11], exec, s[10:11]
	s_cbranch_execz .LBB0_1639
	v_add_u32_e32 v4, -7, v22
	v_mad_i64_i32 v[4:5], s[28:29], v4, s15, v[0:1]
	global_load_dword v5, v[4:5], off
	s_andn2_saveexec_b64 s[10:11], s[10:11]
	s_cbranch_execnz .LBB0_1640

; __device__ __forceinline__ float lo_bf(unsigned w) { return __uint_as_float(w << 16); }
; __device__ __forceinline__ float hi_bf(unsigned w) { return __uint_as_float(w & 0xffff0000u); }
; __device__ __forceinline__ void pool_item(const Params& P, int l, int item, unsigned char* smem) {
;     ...
; #pragma unroll
;                 for (int k = 0; k < WIN - 1 + 16; ++k) {
;                     const int dt = k - (WIN - 1), t = t0 + dt;
;                     if (t >= 0) { const unsigned wv = *(const unsigned*)(proj + (size_t)(R0 + dt) * NIN + c); u0[k] = lo_bf(wv); u1[k] = hi_bf(wv); }
;                     else if (hist) { const float* hp = hist + (size_t)(15 + t) * 1024 + c; u0[k] = hp[0]; u1[k] = hp[1]; }
;                     else { u0[k] = 0.f; u1[k] = 0.f; }
;                 }
.LBB0_1628:
	v_add_u32_e32 v6, -6, v22
	v_mad_i64_i32 v[6:7], s[28:29], v6, s15, v[0:1]
	global_load_dword v7, v[6:7], off
	s_andn2_saveexec_b64 s[10:11], s[10:11]
	s_cbranch_execnz .LBB0_1644

; __device__ __forceinline__ float lo_bf(unsigned w) { return __uint_as_float(w << 16); }
; __device__ __forceinline__ float hi_bf(unsigned w) { return __uint_as_float(w & 0xffff0000u); }
; __device__ __forceinline__ void pool_item(const Params& P, int l, int item, unsigned char* smem) {
;     ...
; #pragma unroll
;                 for (int k = 0; k < WIN - 1 + 16; ++k) {
;                     const int dt = k - (WIN - 1), t = t0 + dt;
;                     if (t >= 0) { const unsigned wv = *(const unsigned*)(proj + (size_t)(R0 + dt) * NIN + c); u0[k] = lo_bf(wv); u1[k] = hi_bf(wv); }
;                     else if (hist) { const float* hp = hist + (size_t)(15 + t) * 1024 + c; u0[k] = hp[0]; u1[k] = hp[1]; }
;                     else { u0[k] = 0.f; u1[k] = 0.f; }
;                 }
.LBB0_1630:
	v_add_u32_e32 v8, -5, v22
	v_mad_i64_i32 v[8:9], s[28:29], v8, s15, v[0:1]
	global_load_dword v9, v[8:9], off
	s_andn2_saveexec_b64 s[10:11], s[10:11]
	s_cbranch_execnz .LBB0_1648

; __device__ __forceinline__ float lo_bf(unsigned w) { return __uint_as_float(w << 16); }
; __device__ __forceinline__ float hi_bf(unsigned w) { return __uint_as_float(w & 0xffff0000u); }
; __device__ __forceinline__ void pool_item(const Params& P, int l, int item, unsigned char* smem) {
;     ...
; #pragma unroll
;                 for (int k = 0; k < WIN - 1 + 16; ++k) {
;                     const int dt = k - (WIN - 1), t = t0 + dt;
;                     if (t >= 0) { const unsigned wv = *(const unsigned*)(proj + (size_t)(R0 + dt) * NIN + c); u0[k] = lo_bf(wv); u1[k] = hi_bf(wv); }
;                     else if (hist) { const float* hp = hist + (size_t)(15 + t) * 1024 + c; u0[k] = hp[0]; u1[k] = hp[1]; }
;                     else { u0[k] = 0.f; u1[k] = 0.f; }
;                 }
.LBB0_1632:
	v_add_u32_e32 v10, -4, v22
	v_mad_i64_i32 v[10:11], s[28:29], v10, s15, v[0:1]
	global_load_dword v11, v[10:11], off
	s_andn2_saveexec_b64 s[10:11], s[10:11]
	s_cbranch_execnz .LBB0_1652

; __device__ __forceinline__ float lo_bf(unsigned w) { return __uint_as_float(w << 16); }
; __device__ __forceinline__ float hi_bf(unsigned w) { return __uint_as_float(w & 0xffff0000u); }
; __device__ __forceinline__ void pool_item(const Params& P, int l, int item, unsigned char* smem) {
;     ...
; #pragma unroll
;                 for (int k = 0; k < WIN - 1 + 16; ++k) {
;                     const int dt = k - (WIN - 1), t = t0 + dt;
;                     if (t >= 0) { const unsigned wv = *(const unsigned*)(proj + (size_t)(R0 + dt) * NIN + c); u0[k] = lo_bf(wv); u1[k] = hi_bf(wv); }
;                     else if (hist) { const float* hp = hist + (size_t)(15 + t) * 1024 + c; u0[k] = hp[0]; u1[k] = hp[1]; }
;                     else { u0[k] = 0.f; u1[k] = 0.f; }
;                 }
.LBB0_1634:
	v_add_u32_e32 v12, -3, v22
	v_mad_i64_i32 v[12:13], s[28:29], v12, s15, v[0:1]
	global_load_dword v13, v[12:13], off
	s_andn2_saveexec_b64 s[10:11], s[10:11]
	s_cbranch_execnz .LBB0_1656

; __device__ __forceinline__ float lo_bf(unsigned w) { return __uint_as_float(w << 16); }
; __device__ __forceinline__ float hi_bf(unsigned w) { return __uint_as_float(w & 0xffff0000u); }
; __device__ __forceinline__ void pool_item(const Params& P, int l, int item, unsigned char* smem) {
;     ...
; #pragma unroll
;                 for (int k = 0; k < WIN - 1 + 16; ++k) {
;                     const int dt = k - (WIN - 1), t = t0 + dt;
;                     if (t >= 0) { const unsigned wv = *(const unsigned*)(proj + (size_t)(R0 + dt) * NIN + c); u0[k] = lo_bf(wv); u1[k] = hi_bf(wv); }
;                     else if (hist) { const float* hp = hist + (size_t)(15 + t) * 1024 + c; u0[k] = hp[0]; u1[k] = hp[1]; }
;                     else { u0[k] = 0.f; u1[k] = 0.f; }
;                 }
.LBB0_1636:
	v_add_u32_e32 v14, -2, v22
	v_mad_i64_i32 v[14:15], s[28:29], v14, s15, v[0:1]
	global_load_dword v15, v[14:15], off
	s_andn2_saveexec_b64 s[10:11], s[10:11]
	s_cbranch_execnz .LBB0_1660

; __device__ __forceinline__ float lo_bf(unsigned w) { return __uint_as_float(w << 16); }
; __device__ __forceinline__ float hi_bf(unsigned w) { return __uint_as_float(w & 0xffff0000u); }
; __device__ __forceinline__ void pool_item(const Params& P, int l, int item, unsigned char* smem) {
;     ...
; #pragma unroll
;                 for (int k = 0; k < WIN - 1 + 16; ++k) {
;                     const int dt = k - (WIN - 1), t = t0 + dt;
;                     if (t >= 0) { const unsigned wv = *(const unsigned*)(proj + (size_t)(R0 + dt) * NIN + c); u0[k] = lo_bf(wv); u1[k] = hi_bf(wv); }
;                     else if (hist) { const float* hp = hist + (size_t)(15 + t) * 1024 + c; u0[k] = hp[0]; u1[k] = hp[1]; }
;                     else { u0[k] = 0.f; u1[k] = 0.f; }
;                 }
.LBB0_1638:
	v_add_u32_e32 v16, -1, v22
	v_mad_i64_i32 v[16:17], s[10:11], v16, s15, v[0:1]
	global_load_dword v17, v[16:17], off
	s_waitcnt vmcnt(0)
	v_lshlrev_b32_e32 v4, 16, v5
	v_and_b32_e32 v5, 0xffff0000, v5
	v_lshlrev_b32_e32 v6, 16, v7
	v_and_b32_e32 v7, 0xffff0000, v7
	v_lshlrev_b32_e32 v8, 16, v9
	v_and_b32_e32 v9, 0xffff0000, v9
	v_lshlrev_b32_e32 v10, 16, v11
	v_and_b32_e32 v11, 0xffff0000, v11
	v_lshlrev_b32_e32 v12, 16, v13
	v_and_b32_e32 v13, 0xffff0000, v13
	v_lshlrev_b32_e32 v14, 16, v15
	v_and_b32_e32 v15, 0xffff0000, v15
	v_lshlrev_b32_e32 v16, 16, v17
	v_and_b32_e32 v17, 0xffff0000, v17
	s_andn2_saveexec_b64 s[6:7], s[6:7]
	s_cbranch_execz .LBB0_1620
	s_branch .LBB0_1664

; __device__ __forceinline__ float lo_bf(unsigned w) { return __uint_as_float(w << 16); }
; __device__ __forceinline__ float hi_bf(unsigned w) { return __uint_as_float(w & 0xffff0000u); }
; __device__ __forceinline__ void pool_item(const Params& P, int l, int item, unsigned char* smem) {
;     ...
; #pragma unroll
;                 for (int k = 0; k < WIN - 1 + 16; ++k) {
;                     const int dt = k - (WIN - 1), t = t0 + dt;
;                     if (t >= 0) { const unsigned wv = *(const unsigned*)(proj + (size_t)(R0 + dt) * NIN + c); u0[k] = lo_bf(wv); u1[k] = hi_bf(wv); }
;                     else if (hist) { const float* hp = hist + (size_t)(15 + t) * 1024 + c; u0[k] = hp[0]; u1[k] = hp[1]; }
;                     else { u0[k] = 0.f; u1[k] = 0.f; }
;                 }
.LBB0_1690:
	s_or_b64 exec, exec, s[4:5]
	v_cmp_ne_u64_e64 s[4:5], 0, v[10:11]
	v_cmp_ne_u32_e64 s[6:7], 0, v12
	s_and_saveexec_b64 s[10:11], s[6:7]
	s_xor_b64 s[10:11], exec, s[10:11]
	s_cbranch_execz .LBB0_1696
	v_add_u32_e32 v4, -3, v14
	v_mad_i64_i32 v[4:5], s[28:29], v4, s15, v[0:1]
	global_load_dword v5, v[4:5], off
	s_andn2_saveexec_b64 s[10:11], s[10:11]
	s_cbranch_execnz .LBB0_1697

; __device__ __forceinline__ float lo_bf(unsigned w) { return __uint_as_float(w << 16); }
; __device__ __forceinline__ float hi_bf(unsigned w) { return __uint_as_float(w & 0xffff0000u); }
; __device__ __forceinline__ void pool_item(const Params& P, int l, int item, unsigned char* smem) {
;     ...
; #pragma unroll
;                 for (int k = 0; k < WIN - 1 + 16; ++k) {
;                     const int dt = k - (WIN - 1), t = t0 + dt;
;                     if (t >= 0) { const unsigned wv = *(const unsigned*)(proj + (size_t)(R0 + dt) * NIN + c); u0[k] = lo_bf(wv); u1[k] = hi_bf(wv); }
;                     else if (hist) { const float* hp = hist + (size_t)(15 + t) * 1024 + c; u0[k] = hp[0]; u1[k] = hp[1]; }
;                     else { u0[k] = 0.f; u1[k] = 0.f; }
;                 }
.LBB0_1693:
	v_add_u32_e32 v6, -2, v14
	v_mad_i64_i32 v[6:7], s[28:29], v6, s15, v[0:1]
	global_load_dword v7, v[6:7], off
	s_andn2_saveexec_b64 s[10:11], s[10:11]
	s_cbranch_execnz .LBB0_1701

; __device__ __forceinline__ float lo_bf(unsigned w) { return __uint_as_float(w << 16); }
; __device__ __forceinline__ float hi_bf(unsigned w) { return __uint_as_float(w & 0xffff0000u); }
; __device__ __forceinline__ void pool_item(const Params& P, int l, int item, unsigned char* smem) {
;     ...
; #pragma unroll
;                 for (int k = 0; k < WIN - 1 + 16; ++k) {
;                     const int dt = k - (WIN - 1), t = t0 + dt;
;                     if (t >= 0) { const unsigned wv = *(const unsigned*)(proj + (size_t)(R0 + dt) * NIN + c); u0[k] = lo_bf(wv); u1[k] = hi_bf(wv); }
;                     else if (hist) { const float* hp = hist + (size_t)(15 + t) * 1024 + c; u0[k] = hp[0]; u1[k] = hp[1]; }
;                     else { u0[k] = 0.f; u1[k] = 0.f; }
;                 }
.LBB0_1695:
	v_add_u32_e32 v8, -1, v14
	v_mad_i64_i32 v[8:9], s[10:11], v8, s15, v[0:1]
	global_load_dword v9, v[8:9], off
	s_waitcnt vmcnt(0)
	v_lshlrev_b32_e32 v4, 16, v5
	v_and_b32_e32 v5, 0xffff0000, v5
	v_lshlrev_b32_e32 v6, 16, v7
	v_and_b32_e32 v7, 0xffff0000, v7
	v_lshlrev_b32_e32 v8, 16, v9
	v_and_b32_e32 v9, 0xffff0000, v9
	s_andn2_saveexec_b64 s[6:7], s[6:7]
	s_cbranch_execz .LBB0_1685
	s_branch .LBB0_1705

; __device__ __forceinline__ unsigned xb_ld(unsigned* p)              { return __hip_atomic_load(p, __ATOMIC_RELAXED, __HIP_MEMORY_SCOPE_AGENT); }
; __device__ __forceinline__ unsigned xb_add(unsigned* p, unsigned v) { return __hip_atomic_fetch_add(p, v, __ATOMIC_RELAXED, __HIP_MEMORY_SCOPE_AGENT); }
; #define XB_SPIN(cond, bar) do { unsigned _sp = 0; while (cond) { __builtin_amdgcn_s_sleep(1); \
;     if ((++_sp & 255u) == 0u) { if (xb_ld(&(bar)[XB_TMO])) break; if (_sp > XB_SPIN_CAP) { atomicAdd(&(bar)[XB_TMO], 1u); break; } } } } while (0)
; __device__ __forceinline__ void xcd_barrier(const XcdBarrier& b) {
;     ...
;         const unsigned old = xb_add(&bar[XB_XSUB(b.x)], 1u);
;         const unsigned gen = old / nloc;
;         if (old + 1u == (gen + 1u) * nloc) {
;             __builtin_amdgcn_fence(__ATOMIC_RELEASE, "agent");
;             asm volatile("s_waitcnt vmcnt(0)" ::: "memory");
;             const unsigned og = xb_add(&bar[XB_TOP], 1u);
;             const unsigned tg = og / nx;
;             if (og + 1u == (tg + 1u) * nx) xb_add(&bar[XB_TOPGEN], 1u);
;             else XB_SPIN(xb_ld(&bar[XB_TOPGEN]) == tg, bar);
;             __builtin_amdgcn_fence(__ATOMIC_ACQUIRE, "agent");
;             xb_add(&bar[XB_XGEN(b.x)], 1u);
;             asm volatile("s_waitcnt vmcnt(0)" ::: "memory");
;         } else {
;             XB_SPIN(xb_ld(&bar[XB_XGEN(b.x)]) == gen, bar);
.LBB0_3727:
	s_or_b64 exec, exec, s[12:13]
	v_cvt_f32_u32_e32 v4, v2
	s_waitcnt vmcnt(0)
	v_readfirstlane_b32 s2, v3
	v_sub_u32_e32 v3, 0, v2
	v_rcp_iflag_f32_e32 v4, v4
	v_add_u32_e32 v5, s2, v1
	v_mul_f32_e32 v4, 0x4f7ffffe, v4
	v_cvt_u32_f32_e32 v4, v4
	v_mul_lo_u32 v1, v3, v4
	v_mul_hi_u32 v1, v4, v1
	v_add_u32_e32 v1, v4, v1
	v_mul_hi_u32 v1, v5, v1
	v_mul_lo_u32 v3, v1, v2
	v_sub_u32_e32 v3, v5, v3
	v_add_u32_e32 v4, 1, v1
	v_cmp_ge_u32_e32 vcc, v3, v2
	s_nop 1
	v_cndmask_b32_e32 v1, v1, v4, vcc
	v_sub_u32_e32 v4, v3, v2
	v_cndmask_b32_e32 v3, v3, v4, vcc
	v_add_u32_e32 v4, 1, v1
	v_cmp_ge_u32_e32 vcc, v3, v2
	v_add_u32_e32 v3, 1, v5
	s_nop 0
	v_cndmask_b32_e32 v1, v1, v4, vcc
	v_mul_lo_u32 v4, v2, v1
	v_add_u32_e32 v2, v4, v2
	v_cmp_ne_u32_e32 vcc, v3, v2
	s_and_saveexec_b64 s[2:3], vcc
	s_xor_b64 s[10:11], exec, s[2:3]
	s_cbranch_execz .LBB0_3741
	s_waitcnt lgkmcnt(0)
	s_cmp_lt_i32 s92, 64
	s_cbranch_scc1 .LBB0_3741
	v_mov_b32_e32 v0, 0x2000
	global_load_dword v0, v0, s[8:9] offset:1024 sc1
	s_add_u32 s18, s8, 0x2400
	s_addc_u32 s19, s9, 0
	s_waitcnt vmcnt(0)
	v_cmp_eq_u32_e32 vcc, v0, v1
	s_and_saveexec_b64 s[12:13], vcc
	s_cbranch_execz .LBB0_3740
	s_mov_b32 s2, 1
	s_mov_b64 s[30:31], 0
	v_mov_b32_e32 v0, 0
	s_branch .LBB0_3731

; __device__ __forceinline__ float lo_bf(unsigned w) { return __uint_as_float(w << 16); }
; __device__ __forceinline__ float hi_bf(unsigned w) { return __uint_as_float(w & 0xffff0000u); }
; __device__ __forceinline__ void pool_item(const Params& P, int l, int item, unsigned char* smem) {
;     ...
; #pragma unroll
;                 for (int k = 0; k < WIN - 1 + 16; ++k) {
;                     const int dt = k - (WIN - 1), t = t0 + dt;
;                     if (t >= 0) { const unsigned wv = *(const unsigned*)(proj + (size_t)(R0 + dt) * NIN + c); u0[k] = lo_bf(wv); u1[k] = hi_bf(wv); }
;                     else if (hist) { const float* hp = hist + (size_t)(15 + t) * 1024 + c; u0[k] = hp[0]; u1[k] = hp[1]; }
;                     else { u0[k] = 0.f; u1[k] = 0.f; }
;                 }
.LBB0_3833:
	s_or_b64 exec, exec, s[6:7]
	v_cmp_ne_u64_e64 s[6:7], 0, v[18:19]
	v_cmp_ne_u32_e64 s[8:9], 0, v37
	s_and_saveexec_b64 s[4:5], s[8:9]
	s_xor_b64 s[12:13], exec, s[4:5]
	s_cbranch_execz .LBB0_3863
	v_add_u32_e32 v4, -15, v39
	v_mad_i64_i32 v[4:5], s[4:5], v4, s21, v[0:1]
	global_load_dword v5, v[4:5], off
	s_andn2_saveexec_b64 s[12:13], s[12:13]
	s_cbranch_execnz .LBB0_3864

; __device__ __forceinline__ float lo_bf(unsigned w) { return __uint_as_float(w << 16); }
; __device__ __forceinline__ float hi_bf(unsigned w) { return __uint_as_float(w & 0xffff0000u); }
; __device__ __forceinline__ void pool_item(const Params& P, int l, int item, unsigned char* smem) {
;     ...
; #pragma unroll
;                 for (int k = 0; k < WIN - 1 + 16; ++k) {
;                     const int dt = k - (WIN - 1), t = t0 + dt;
;                     if (t >= 0) { const unsigned wv = *(const unsigned*)(proj + (size_t)(R0 + dt) * NIN + c); u0[k] = lo_bf(wv); u1[k] = hi_bf(wv); }
;                     else if (hist) { const float* hp = hist + (size_t)(15 + t) * 1024 + c; u0[k] = hp[0]; u1[k] = hp[1]; }
;                     else { u0[k] = 0.f; u1[k] = 0.f; }
;                 }
.LBB0_3836:
	v_add_u32_e32 v6, -14, v39
	v_mad_i64_i32 v[6:7], s[4:5], v6, s21, v[0:1]
	global_load_dword v7, v[6:7], off
	s_andn2_saveexec_b64 s[12:13], s[12:13]
	s_cbranch_execnz .LBB0_3868

; __device__ __forceinline__ float lo_bf(unsigned w) { return __uint_as_float(w << 16); }
; __device__ __forceinline__ float hi_bf(unsigned w) { return __uint_as_float(w & 0xffff0000u); }
; __device__ __forceinline__ void pool_item(const Params& P, int l, int item, unsigned char* smem) {
;     ...
; #pragma unroll
;                 for (int k = 0; k < WIN - 1 + 16; ++k) {
;                     const int dt = k - (WIN - 1), t = t0 + dt;
;                     if (t >= 0) { const unsigned wv = *(const unsigned*)(proj + (size_t)(R0 + dt) * NIN + c); u0[k] = lo_bf(wv); u1[k] = hi_bf(wv); }
;                     else if (hist) { const float* hp = hist + (size_t)(15 + t) * 1024 + c; u0[k] = hp[0]; u1[k] = hp[1]; }
;                     else { u0[k] = 0.f; u1[k] = 0.f; }
;                 }
.LBB0_3838:
	v_add_u32_e32 v8, -13, v39
	v_mad_i64_i32 v[8:9], s[4:5], v8, s21, v[0:1]
	global_load_dword v9, v[8:9], off
	s_andn2_saveexec_b64 s[12:13], s[12:13]
	s_cbranch_execnz .LBB0_3872

; __device__ __forceinline__ float lo_bf(unsigned w) { return __uint_as_float(w << 16); }
; __device__ __forceinline__ float hi_bf(unsigned w) { return __uint_as_float(w & 0xffff0000u); }
; __device__ __forceinline__ void pool_item(const Params& P, int l, int item, unsigned char* smem) {
;     ...
; #pragma unroll
;                 for (int k = 0; k < WIN - 1 + 16; ++k) {
;                     const int dt = k - (WIN - 1), t = t0 + dt;
;                     if (t >= 0) { const unsigned wv = *(const unsigned*)(proj + (size_t)(R0 + dt) * NIN + c); u0[k] = lo_bf(wv); u1[k] = hi_bf(wv); }
;                     else if (hist) { const float* hp = hist + (size_t)(15 + t) * 1024 + c; u0[k] = hp[0]; u1[k] = hp[1]; }
;                     else { u0[k] = 0.f; u1[k] = 0.f; }
;                 }
.LBB0_3840:
	v_add_u32_e32 v10, -12, v39
	v_mad_i64_i32 v[10:11], s[4:5], v10, s21, v[0:1]
	global_load_dword v11, v[10:11], off
	s_andn2_saveexec_b64 s[12:13], s[12:13]
	s_cbranch_execnz .LBB0_3876

; __device__ __forceinline__ float lo_bf(unsigned w) { return __uint_as_float(w << 16); }
; __device__ __forceinline__ float hi_bf(unsigned w) { return __uint_as_float(w & 0xffff0000u); }
; __device__ __forceinline__ void pool_item(const Params& P, int l, int item, unsigned char* smem) {
;     ...
; #pragma unroll
;                 for (int k = 0; k < WIN - 1 + 16; ++k) {
;                     const int dt = k - (WIN - 1), t = t0 + dt;
;                     if (t >= 0) { const unsigned wv = *(const unsigned*)(proj + (size_t)(R0 + dt) * NIN + c); u0[k] = lo_bf(wv); u1[k] = hi_bf(wv); }
;                     else if (hist) { const float* hp = hist + (size_t)(15 + t) * 1024 + c; u0[k] = hp[0]; u1[k] = hp[1]; }
;                     else { u0[k] = 0.f; u1[k] = 0.f; }
;                 }
.LBB0_3842:
	v_add_u32_e32 v12, -11, v39
	v_mad_i64_i32 v[12:13], s[4:5], v12, s21, v[0:1]
	global_load_dword v13, v[12:13], off
	s_andn2_saveexec_b64 s[12:13], s[12:13]
	s_cbranch_execnz .LBB0_3880

; __device__ __forceinline__ float lo_bf(unsigned w) { return __uint_as_float(w << 16); }
; __device__ __forceinline__ float hi_bf(unsigned w) { return __uint_as_float(w & 0xffff0000u); }
; __device__ __forceinline__ void pool_item(const Params& P, int l, int item, unsigned char* smem) {
;     ...
; #pragma unroll
;                 for (int k = 0; k < WIN - 1 + 16; ++k) {
;                     const int dt = k - (WIN - 1), t = t0 + dt;
;                     if (t >= 0) { const unsigned wv = *(const unsigned*)(proj + (size_t)(R0 + dt) * NIN + c); u0[k] = lo_bf(wv); u1[k] = hi_bf(wv); }
;                     else if (hist) { const float* hp = hist + (size_t)(15 + t) * 1024 + c; u0[k] = hp[0]; u1[k] = hp[1]; }
;                     else { u0[k] = 0.f; u1[k] = 0.f; }
;                 }
.LBB0_3844:
	v_add_u32_e32 v14, -10, v39
	v_mad_i64_i32 v[14:15], s[4:5], v14, s21, v[0:1]
	global_load_dword v15, v[14:15], off
	s_andn2_saveexec_b64 s[12:13], s[12:13]
	s_cbranch_execnz .LBB0_3884

; __device__ __forceinline__ float lo_bf(unsigned w) { return __uint_as_float(w << 16); }
; __device__ __forceinline__ float hi_bf(unsigned w) { return __uint_as_float(w & 0xffff0000u); }
; __device__ __forceinline__ void pool_item(const Params& P, int l, int item, unsigned char* smem) {
;     ...
; #pragma unroll
;                 for (int k = 0; k < WIN - 1 + 16; ++k) {
;                     const int dt = k - (WIN - 1), t = t0 + dt;
;                     if (t >= 0) { const unsigned wv = *(const unsigned*)(proj + (size_t)(R0 + dt) * NIN + c); u0[k] = lo_bf(wv); u1[k] = hi_bf(wv); }
;                     else if (hist) { const float* hp = hist + (size_t)(15 + t) * 1024 + c; u0[k] = hp[0]; u1[k] = hp[1]; }
;                     else { u0[k] = 0.f; u1[k] = 0.f; }
;                 }
.LBB0_3846:
	v_add_u32_e32 v16, -9, v39
	v_mad_i64_i32 v[16:17], s[4:5], v16, s21, v[0:1]
	global_load_dword v17, v[16:17], off
	s_andn2_saveexec_b64 s[12:13], s[12:13]
	s_cbranch_execnz .LBB0_3888

; __device__ __forceinline__ float lo_bf(unsigned w) { return __uint_as_float(w << 16); }
; __device__ __forceinline__ float hi_bf(unsigned w) { return __uint_as_float(w & 0xffff0000u); }
; __device__ __forceinline__ void pool_item(const Params& P, int l, int item, unsigned char* smem) {
;     ...
; #pragma unroll
;                 for (int k = 0; k < WIN - 1 + 16; ++k) {
;                     const int dt = k - (WIN - 1), t = t0 + dt;
;                     if (t >= 0) { const unsigned wv = *(const unsigned*)(proj + (size_t)(R0 + dt) * NIN + c); u0[k] = lo_bf(wv); u1[k] = hi_bf(wv); }
;                     else if (hist) { const float* hp = hist + (size_t)(15 + t) * 1024 + c; u0[k] = hp[0]; u1[k] = hp[1]; }
;                     else { u0[k] = 0.f; u1[k] = 0.f; }
;                 }
.LBB0_3848:
	v_add_u32_e32 v20, -8, v39
	v_mad_i64_i32 v[20:21], s[4:5], v20, s21, v[0:1]
	global_load_dword v21, v[20:21], off
	s_andn2_saveexec_b64 s[12:13], s[12:13]
	s_cbranch_execnz .LBB0_3892

; __device__ __forceinline__ float lo_bf(unsigned w) { return __uint_as_float(w << 16); }
; __device__ __forceinline__ float hi_bf(unsigned w) { return __uint_as_float(w & 0xffff0000u); }
; __device__ __forceinline__ void pool_item(const Params& P, int l, int item, unsigned char* smem) {
;     ...
; #pragma unroll
;                 for (int k = 0; k < WIN - 1 + 16; ++k) {
;                     const int dt = k - (WIN - 1), t = t0 + dt;
;                     if (t >= 0) { const unsigned wv = *(const unsigned*)(proj + (size_t)(R0 + dt) * NIN + c); u0[k] = lo_bf(wv); u1[k] = hi_bf(wv); }
;                     else if (hist) { const float* hp = hist + (size_t)(15 + t) * 1024 + c; u0[k] = hp[0]; u1[k] = hp[1]; }
;                     else { u0[k] = 0.f; u1[k] = 0.f; }
;                 }
.LBB0_3850:
	v_add_u32_e32 v22, -7, v39
	v_mad_i64_i32 v[22:23], s[4:5], v22, s21, v[0:1]
	global_load_dword v23, v[22:23], off
	s_andn2_saveexec_b64 s[12:13], s[12:13]
	s_cbranch_execnz .LBB0_3896

; __device__ __forceinline__ float lo_bf(unsigned w) { return __uint_as_float(w << 16); }
; __device__ __forceinline__ float hi_bf(unsigned w) { return __uint_as_float(w & 0xffff0000u); }
; __device__ __forceinline__ void pool_item(const Params& P, int l, int item, unsigned char* smem) {
;     ...
; #pragma unroll
;                 for (int k = 0; k < WIN - 1 + 16; ++k) {
;                     const int dt = k - (WIN - 1), t = t0 + dt;
;                     if (t >= 0) { const unsigned wv = *(const unsigned*)(proj + (size_t)(R0 + dt) * NIN + c); u0[k] = lo_bf(wv); u1[k] = hi_bf(wv); }
;                     else if (hist) { const float* hp = hist + (size_t)(15 + t) * 1024 + c; u0[k] = hp[0]; u1[k] = hp[1]; }
;                     else { u0[k] = 0.f; u1[k] = 0.f; }
;                 }
.LBB0_3852:
	v_add_u32_e32 v24, -6, v39
	v_mad_i64_i32 v[24:25], s[4:5], v24, s21, v[0:1]
	global_load_dword v25, v[24:25], off
	s_andn2_saveexec_b64 s[12:13], s[12:13]
	s_cbranch_execnz .LBB0_3900

; __device__ __forceinline__ float lo_bf(unsigned w) { return __uint_as_float(w << 16); }
; __device__ __forceinline__ float hi_bf(unsigned w) { return __uint_as_float(w & 0xffff0000u); }
; __device__ __forceinline__ void pool_item(const Params& P, int l, int item, unsigned char* smem) {
;     ...
; #pragma unroll
;                 for (int k = 0; k < WIN - 1 + 16; ++k) {
;                     const int dt = k - (WIN - 1), t = t0 + dt;
;                     if (t >= 0) { const unsigned wv = *(const unsigned*)(proj + (size_t)(R0 + dt) * NIN + c); u0[k] = lo_bf(wv); u1[k] = hi_bf(wv); }
;                     else if (hist) { const float* hp = hist + (size_t)(15 + t) * 1024 + c; u0[k] = hp[0]; u1[k] = hp[1]; }
;                     else { u0[k] = 0.f; u1[k] = 0.f; }
;                 }
.LBB0_3854:
	v_add_u32_e32 v26, -5, v39
	v_mad_i64_i32 v[26:27], s[4:5], v26, s21, v[0:1]
	global_load_dword v27, v[26:27], off
	s_andn2_saveexec_b64 s[12:13], s[12:13]
	s_cbranch_execnz .LBB0_3904

; __device__ __forceinline__ float lo_bf(unsigned w) { return __uint_as_float(w << 16); }
; __device__ __forceinline__ float hi_bf(unsigned w) { return __uint_as_float(w & 0xffff0000u); }
; __device__ __forceinline__ void pool_item(const Params& P, int l, int item, unsigned char* smem) {
;     ...
; #pragma unroll
;                 for (int k = 0; k < WIN - 1 + 16; ++k) {
;                     const int dt = k - (WIN - 1), t = t0 + dt;
;                     if (t >= 0) { const unsigned wv = *(const unsigned*)(proj + (size_t)(R0 + dt) * NIN + c); u0[k] = lo_bf(wv); u1[k] = hi_bf(wv); }
;                     else if (hist) { const float* hp = hist + (size_t)(15 + t) * 1024 + c; u0[k] = hp[0]; u1[k] = hp[1]; }
;                     else { u0[k] = 0.f; u1[k] = 0.f; }
;                 }
.LBB0_3856:
	v_add_u32_e32 v28, -4, v39
	v_mad_i64_i32 v[28:29], s[4:5], v28, s21, v[0:1]
	global_load_dword v29, v[28:29], off
	s_andn2_saveexec_b64 s[12:13], s[12:13]
	s_cbranch_execnz .LBB0_3908

; __device__ __forceinline__ float lo_bf(unsigned w) { return __uint_as_float(w << 16); }
; __device__ __forceinline__ float hi_bf(unsigned w) { return __uint_as_float(w & 0xffff0000u); }
; __device__ __forceinline__ void pool_item(const Params& P, int l, int item, unsigned char* smem) {
;     ...
; #pragma unroll
;                 for (int k = 0; k < WIN - 1 + 16; ++k) {
;                     const int dt = k - (WIN - 1), t = t0 + dt;
;                     if (t >= 0) { const unsigned wv = *(const unsigned*)(proj + (size_t)(R0 + dt) * NIN + c); u0[k] = lo_bf(wv); u1[k] = hi_bf(wv); }
;                     else if (hist) { const float* hp = hist + (size_t)(15 + t) * 1024 + c; u0[k] = hp[0]; u1[k] = hp[1]; }
;                     else { u0[k] = 0.f; u1[k] = 0.f; }
;                 }
.LBB0_3858:
	v_add_u32_e32 v30, -3, v39
	v_mad_i64_i32 v[30:31], s[4:5], v30, s21, v[0:1]
	global_load_dword v31, v[30:31], off
	s_andn2_saveexec_b64 s[12:13], s[12:13]
	s_cbranch_execnz .LBB0_3912

; __device__ __forceinline__ float lo_bf(unsigned w) { return __uint_as_float(w << 16); }
; __device__ __forceinline__ float hi_bf(unsigned w) { return __uint_as_float(w & 0xffff0000u); }
; __device__ __forceinline__ void pool_item(const Params& P, int l, int item, unsigned char* smem) {
;     ...
; #pragma unroll
;                 for (int k = 0; k < WIN - 1 + 16; ++k) {
;                     const int dt = k - (WIN - 1), t = t0 + dt;
;                     if (t >= 0) { const unsigned wv = *(const unsigned*)(proj + (size_t)(R0 + dt) * NIN + c); u0[k] = lo_bf(wv); u1[k] = hi_bf(wv); }
;                     else if (hist) { const float* hp = hist + (size_t)(15 + t) * 1024 + c; u0[k] = hp[0]; u1[k] = hp[1]; }
;                     else { u0[k] = 0.f; u1[k] = 0.f; }
;                 }
.LBB0_3860:
	v_add_u32_e32 v32, -2, v39
	v_mad_i64_i32 v[32:33], s[4:5], v32, s21, v[0:1]
	global_load_dword v33, v[32:33], off
	s_andn2_saveexec_b64 s[12:13], s[12:13]
	s_cbranch_execnz .LBB0_3916

; __device__ __forceinline__ float lo_bf(unsigned w) { return __uint_as_float(w << 16); }
; __device__ __forceinline__ float hi_bf(unsigned w) { return __uint_as_float(w & 0xffff0000u); }
; __device__ __forceinline__ void pool_item(const Params& P, int l, int item, unsigned char* smem) {
;     ...
; #pragma unroll
;                 for (int k = 0; k < WIN - 1 + 16; ++k) {
;                     const int dt = k - (WIN - 1), t = t0 + dt;
;                     if (t >= 0) { const unsigned wv = *(const unsigned*)(proj + (size_t)(R0 + dt) * NIN + c); u0[k] = lo_bf(wv); u1[k] = hi_bf(wv); }
;                     else if (hist) { const float* hp = hist + (size_t)(15 + t) * 1024 + c; u0[k] = hp[0]; u1[k] = hp[1]; }
;                     else { u0[k] = 0.f; u1[k] = 0.f; }
;                 }
.LBB0_3862:
	v_add_u32_e32 v18, -1, v39
	v_mad_i64_i32 v[18:19], s[4:5], v18, s21, v[0:1]
	global_load_dword v18, v[18:19], off
	s_waitcnt vmcnt(0)
	v_lshlrev_b32_e32 v4, 16, v5
	v_and_b32_e32 v5, 0xffff0000, v5
	v_lshlrev_b32_e32 v6, 16, v7
	v_and_b32_e32 v7, 0xffff0000, v7
	v_lshlrev_b32_e32 v8, 16, v9
	v_and_b32_e32 v9, 0xffff0000, v9
	v_lshlrev_b32_e32 v10, 16, v11
	v_and_b32_e32 v11, 0xffff0000, v11
	v_lshlrev_b32_e32 v12, 16, v13
	v_and_b32_e32 v13, 0xffff0000, v13
	v_lshlrev_b32_e32 v14, 16, v15
	v_and_b32_e32 v15, 0xffff0000, v15
	v_lshlrev_b32_e32 v16, 16, v17
	v_and_b32_e32 v17, 0xffff0000, v17
	v_lshlrev_b32_e32 v20, 16, v21
	v_and_b32_e32 v21, 0xffff0000, v21
	v_lshlrev_b32_e32 v22, 16, v23
	v_and_b32_e32 v23, 0xffff0000, v23
	v_lshlrev_b32_e32 v24, 16, v25
	v_and_b32_e32 v25, 0xffff0000, v25
	v_lshlrev_b32_e32 v26, 16, v27
	v_and_b32_e32 v27, 0xffff0000, v27
	v_lshlrev_b32_e32 v28, 16, v29
	v_and_b32_e32 v29, 0xffff0000, v29
	v_lshlrev_b32_e32 v30, 16, v31
	v_and_b32_e32 v31, 0xffff0000, v31
	v_lshlrev_b32_e32 v32, 16, v33
	v_and_b32_e32 v33, 0xffff0000, v33
	v_lshlrev_b32_e32 v34, 16, v18
	v_and_b32_e32 v35, 0xffff0000, v18
	s_andn2_saveexec_b64 s[8:9], s[8:9]
	s_cbranch_execz .LBB0_3828
	s_branch .LBB0_3920

; __device__ __forceinline__ float lo_bf(unsigned w) { return __uint_as_float(w << 16); }
; __device__ __forceinline__ float hi_bf(unsigned w) { return __uint_as_float(w & 0xffff0000u); }
; __device__ __forceinline__ void pool_item(const Params& P, int l, int item, unsigned char* smem) {
;     ...
; #pragma unroll
;                 for (int k = 0; k < WIN - 1 + 16; ++k) {
;                     const int dt = k - (WIN - 1), t = t0 + dt;
;                     if (t >= 0) { const unsigned wv = *(const unsigned*)(proj + (size_t)(R0 + dt) * NIN + c); u0[k] = lo_bf(wv); u1[k] = hi_bf(wv); }
;                     else if (hist) { const float* hp = hist + (size_t)(15 + t) * 1024 + c; u0[k] = hp[0]; u1[k] = hp[1]; }
;                     else { u0[k] = 0.f; u1[k] = 0.f; }
;                 }
.LBB0_3932:
	s_or_b64 exec, exec, s[6:7]
	v_cmp_ne_u64_e64 s[6:7], 0, v[16:17]
	v_cmp_ne_u32_e64 s[8:9], 0, v20
	s_and_saveexec_b64 s[4:5], s[8:9]
	s_xor_b64 s[12:13], exec, s[4:5]
	s_cbranch_execz .LBB0_3946
	v_add_u32_e32 v4, -7, v22
	v_mad_i64_i32 v[4:5], s[4:5], v4, s21, v[0:1]
	global_load_dword v5, v[4:5], off
	s_andn2_saveexec_b64 s[12:13], s[12:13]
	s_cbranch_execnz .LBB0_3947

; __device__ __forceinline__ float lo_bf(unsigned w) { return __uint_as_float(w << 16); }
; __device__ __forceinline__ float hi_bf(unsigned w) { return __uint_as_float(w & 0xffff0000u); }
; __device__ __forceinline__ void pool_item(const Params& P, int l, int item, unsigned char* smem) {
;     ...
; #pragma unroll
;                 for (int k = 0; k < WIN - 1 + 16; ++k) {
;                     const int dt = k - (WIN - 1), t = t0 + dt;
;                     if (t >= 0) { const unsigned wv = *(const unsigned*)(proj + (size_t)(R0 + dt) * NIN + c); u0[k] = lo_bf(wv); u1[k] = hi_bf(wv); }
;                     else if (hist) { const float* hp = hist + (size_t)(15 + t) * 1024 + c; u0[k] = hp[0]; u1[k] = hp[1]; }
;                     else { u0[k] = 0.f; u1[k] = 0.f; }
;                 }
.LBB0_3935:
	v_add_u32_e32 v6, -6, v22
	v_mad_i64_i32 v[6:7], s[4:5], v6, s21, v[0:1]
	global_load_dword v7, v[6:7], off
	s_andn2_saveexec_b64 s[12:13], s[12:13]
	s_cbranch_execnz .LBB0_3951

; __device__ __forceinline__ float lo_bf(unsigned w) { return __uint_as_float(w << 16); }
; __device__ __forceinline__ float hi_bf(unsigned w) { return __uint_as_float(w & 0xffff0000u); }
; __device__ __forceinline__ void pool_item(const Params& P, int l, int item, unsigned char* smem) {
;     ...
; #pragma unroll
;                 for (int k = 0; k < WIN - 1 + 16; ++k) {
;                     const int dt = k - (WIN - 1), t = t0 + dt;
;                     if (t >= 0) { const unsigned wv = *(const unsigned*)(proj + (size_t)(R0 + dt) * NIN + c); u0[k] = lo_bf(wv); u1[k] = hi_bf(wv); }
;                     else if (hist) { const float* hp = hist + (size_t)(15 + t) * 1024 + c; u0[k] = hp[0]; u1[k] = hp[1]; }
;                     else { u0[k] = 0.f; u1[k] = 0.f; }
;                 }
.LBB0_3937:
	v_add_u32_e32 v8, -5, v22
	v_mad_i64_i32 v[8:9], s[4:5], v8, s21, v[0:1]
	global_load_dword v9, v[8:9], off
	s_andn2_saveexec_b64 s[12:13], s[12:13]
	s_cbranch_execnz .LBB0_3955

; __device__ __forceinline__ float lo_bf(unsigned w) { return __uint_as_float(w << 16); }
; __device__ __forceinline__ float hi_bf(unsigned w) { return __uint_as_float(w & 0xffff0000u); }
; __device__ __forceinline__ void pool_item(const Params& P, int l, int item, unsigned char* smem) {
;     ...
; #pragma unroll
;                 for (int k = 0; k < WIN - 1 + 16; ++k) {
;                     const int dt = k - (WIN - 1), t = t0 + dt;
;                     if (t >= 0) { const unsigned wv = *(const unsigned*)(proj + (size_t)(R0 + dt) * NIN + c); u0[k] = lo_bf(wv); u1[k] = hi_bf(wv); }
;                     else if (hist) { const float* hp = hist + (size_t)(15 + t) * 1024 + c; u0[k] = hp[0]; u1[k] = hp[1]; }
;                     else { u0[k] = 0.f; u1[k] = 0.f; }
;                 }
.LBB0_3939:
	v_add_u32_e32 v10, -4, v22
	v_mad_i64_i32 v[10:11], s[4:5], v10, s21, v[0:1]
	global_load_dword v11, v[10:11], off
	s_andn2_saveexec_b64 s[12:13], s[12:13]
	s_cbranch_execnz .LBB0_3959

; __device__ __forceinline__ float lo_bf(unsigned w) { return __uint_as_float(w << 16); }
; __device__ __forceinline__ float hi_bf(unsigned w) { return __uint_as_float(w & 0xffff0000u); }
; __device__ __forceinline__ void pool_item(const Params& P, int l, int item, unsigned char* smem) {
;     ...
; #pragma unroll
;                 for (int k = 0; k < WIN - 1 + 16; ++k) {
;                     const int dt = k - (WIN - 1), t = t0 + dt;
;                     if (t >= 0) { const unsigned wv = *(const unsigned*)(proj + (size_t)(R0 + dt) * NIN + c); u0[k] = lo_bf(wv); u1[k] = hi_bf(wv); }
;                     else if (hist) { const float* hp = hist + (size_t)(15 + t) * 1024 + c; u0[k] = hp[0]; u1[k] = hp[1]; }
;                     else { u0[k] = 0.f; u1[k] = 0.f; }
;                 }
.LBB0_3941:
	v_add_u32_e32 v12, -3, v22
	v_mad_i64_i32 v[12:13], s[4:5], v12, s21, v[0:1]
	global_load_dword v13, v[12:13], off
	s_andn2_saveexec_b64 s[12:13], s[12:13]
	s_cbranch_execnz .LBB0_3963

; __device__ __forceinline__ float lo_bf(unsigned w) { return __uint_as_float(w << 16); }
; __device__ __forceinline__ float hi_bf(unsigned w) { return __uint_as_float(w & 0xffff0000u); }
; __device__ __forceinline__ void pool_item(const Params& P, int l, int item, unsigned char* smem) {
;     ...
; #pragma unroll
;                 for (int k = 0; k < WIN - 1 + 16; ++k) {
;                     const int dt = k - (WIN - 1), t = t0 + dt;
;                     if (t >= 0) { const unsigned wv = *(const unsigned*)(proj + (size_t)(R0 + dt) * NIN + c); u0[k] = lo_bf(wv); u1[k] = hi_bf(wv); }
;                     else if (hist) { const float* hp = hist + (size_t)(15 + t) * 1024 + c; u0[k] = hp[0]; u1[k] = hp[1]; }
;                     else { u0[k] = 0.f; u1[k] = 0.f; }
;                 }
.LBB0_3943:
	v_add_u32_e32 v14, -2, v22
	v_mad_i64_i32 v[14:15], s[4:5], v14, s21, v[0:1]
	global_load_dword v15, v[14:15], off
	s_andn2_saveexec_b64 s[12:13], s[12:13]
	s_cbranch_execnz .LBB0_3967

; __device__ __forceinline__ float lo_bf(unsigned w) { return __uint_as_float(w << 16); }
; __device__ __forceinline__ float hi_bf(unsigned w) { return __uint_as_float(w & 0xffff0000u); }
; __device__ __forceinline__ void pool_item(const Params& P, int l, int item, unsigned char* smem) {
;     ...
; #pragma unroll
;                 for (int k = 0; k < WIN - 1 + 16; ++k) {
;                     const int dt = k - (WIN - 1), t = t0 + dt;
;                     if (t >= 0) { const unsigned wv = *(const unsigned*)(proj + (size_t)(R0 + dt) * NIN + c); u0[k] = lo_bf(wv); u1[k] = hi_bf(wv); }
;                     else if (hist) { const float* hp = hist + (size_t)(15 + t) * 1024 + c; u0[k] = hp[0]; u1[k] = hp[1]; }
;                     else { u0[k] = 0.f; u1[k] = 0.f; }
;                 }
.LBB0_3945:
	v_add_u32_e32 v16, -1, v22
	v_mad_i64_i32 v[16:17], s[4:5], v16, s21, v[0:1]
	global_load_dword v16, v[16:17], off
	s_waitcnt vmcnt(0)
	v_lshlrev_b32_e32 v4, 16, v5
	v_and_b32_e32 v5, 0xffff0000, v5
	v_lshlrev_b32_e32 v6, 16, v7
	v_and_b32_e32 v7, 0xffff0000, v7
	v_lshlrev_b32_e32 v8, 16, v9
	v_and_b32_e32 v9, 0xffff0000, v9
	v_lshlrev_b32_e32 v10, 16, v11
	v_and_b32_e32 v11, 0xffff0000, v11
	v_lshlrev_b32_e32 v12, 16, v13
	v_and_b32_e32 v13, 0xffff0000, v13
	v_lshlrev_b32_e32 v14, 16, v15
	v_and_b32_e32 v15, 0xffff0000, v15
	v_lshlrev_b32_e32 v18, 16, v16
	v_and_b32_e32 v19, 0xffff0000, v16
	s_andn2_saveexec_b64 s[8:9], s[8:9]
	s_cbranch_execz .LBB0_3927
	s_branch .LBB0_3971

; __device__ __forceinline__ float lo_bf(unsigned w) { return __uint_as_float(w << 16); }
; __device__ __forceinline__ float hi_bf(unsigned w) { return __uint_as_float(w & 0xffff0000u); }
; __device__ __forceinline__ void pool_item(const Params& P, int l, int item, unsigned char* smem) {
;     ...
; #pragma unroll
;                 for (int k = 0; k < WIN - 1 + 16; ++k) {
;                     const int dt = k - (WIN - 1), t = t0 + dt;
;                     if (t >= 0) { const unsigned wv = *(const unsigned*)(proj + (size_t)(R0 + dt) * NIN + c); u0[k] = lo_bf(wv); u1[k] = hi_bf(wv); }
;                     else if (hist) { const float* hp = hist + (size_t)(15 + t) * 1024 + c; u0[k] = hp[0]; u1[k] = hp[1]; }
;                     else { u0[k] = 0.f; u1[k] = 0.f; }
;                 }
.LBB0_3997:
	s_or_b64 exec, exec, s[6:7]
	v_cmp_ne_u64_e64 s[6:7], 0, v[10:11]
	v_cmp_ne_u32_e64 s[8:9], 0, v12
	s_and_saveexec_b64 s[4:5], s[8:9]
	s_xor_b64 s[12:13], exec, s[4:5]
	s_cbranch_execz .LBB0_4003
	v_add_u32_e32 v4, -3, v14
	v_mad_i64_i32 v[4:5], s[4:5], v4, s21, v[0:1]
	global_load_dword v5, v[4:5], off
	s_andn2_saveexec_b64 s[12:13], s[12:13]
	s_cbranch_execnz .LBB0_4004

; __device__ __forceinline__ float lo_bf(unsigned w) { return __uint_as_float(w << 16); }
; __device__ __forceinline__ float hi_bf(unsigned w) { return __uint_as_float(w & 0xffff0000u); }
; __device__ __forceinline__ void pool_item(const Params& P, int l, int item, unsigned char* smem) {
;     ...
; #pragma unroll
;                 for (int k = 0; k < WIN - 1 + 16; ++k) {
;                     const int dt = k - (WIN - 1), t = t0 + dt;
;                     if (t >= 0) { const unsigned wv = *(const unsigned*)(proj + (size_t)(R0 + dt) * NIN + c); u0[k] = lo_bf(wv); u1[k] = hi_bf(wv); }
;                     else if (hist) { const float* hp = hist + (size_t)(15 + t) * 1024 + c; u0[k] = hp[0]; u1[k] = hp[1]; }
;                     else { u0[k] = 0.f; u1[k] = 0.f; }
;                 }
.LBB0_4000:
	v_add_u32_e32 v6, -2, v14
	v_mad_i64_i32 v[6:7], s[4:5], v6, s21, v[0:1]
	global_load_dword v7, v[6:7], off
	s_andn2_saveexec_b64 s[12:13], s[12:13]
	s_cbranch_execnz .LBB0_4008

; __device__ __forceinline__ float lo_bf(unsigned w) { return __uint_as_float(w << 16); }
; __device__ __forceinline__ float hi_bf(unsigned w) { return __uint_as_float(w & 0xffff0000u); }
; __device__ __forceinline__ void pool_item(const Params& P, int l, int item, unsigned char* smem) {
;     ...
; #pragma unroll
;                 for (int k = 0; k < WIN - 1 + 16; ++k) {
;                     const int dt = k - (WIN - 1), t = t0 + dt;
;                     if (t >= 0) { const unsigned wv = *(const unsigned*)(proj + (size_t)(R0 + dt) * NIN + c); u0[k] = lo_bf(wv); u1[k] = hi_bf(wv); }
;                     else if (hist) { const float* hp = hist + (size_t)(15 + t) * 1024 + c; u0[k] = hp[0]; u1[k] = hp[1]; }
;                     else { u0[k] = 0.f; u1[k] = 0.f; }
;                 }
.LBB0_4002:
	v_add_u32_e32 v8, -1, v14
	v_mad_i64_i32 v[8:9], s[4:5], v8, s21, v[0:1]
	global_load_dword v9, v[8:9], off
	s_waitcnt vmcnt(0)
	v_lshlrev_b32_e32 v4, 16, v5
	v_and_b32_e32 v5, 0xffff0000, v5
	v_lshlrev_b32_e32 v6, 16, v7
	v_and_b32_e32 v7, 0xffff0000, v7
	v_lshlrev_b32_e32 v8, 16, v9
	v_and_b32_e32 v9, 0xffff0000, v9
	s_andn2_saveexec_b64 s[8:9], s[8:9]
	s_cbranch_execz .LBB0_3992
	s_branch .LBB0_4012
